# phase 11 LN1 write pass: ln_w/ln_b loads of the next column step hoisted above the current step's stores into spare registers, counted vmcnt(3) wait
# baseline (speedup 1.0000x reference)
.LBB0_849:
	v_lshl_add_u64 v[54:55], s[92:93], 0, v[10:11]
	global_load_dwordx4 v[0:3], v[14:15], off
	global_load_dwordx4 v[4:7], v[16:17], off
	global_load_dwordx4 v[60:63], v[54:55], off
	global_load_dwordx4 v[68:71], v[54:55], off offset:1024
	global_load_dwordx4 v[84:87], v[54:55], off offset:2048
	global_load_dwordx4 v[88:91], v[54:55], off offset:3072
	v_add_co_u32_e32 v104, vcc, s33, v54
	v_lshl_add_u64 v[64:65], s[94:95], 0, v[10:11]
	s_nop 0
	v_addc_co_u32_e32 v105, vcc, 0, v55, vcc
	global_load_dwordx4 v[92:95], v[104:105], off
	global_load_dwordx4 v[96:99], v[104:105], off offset:1024
	global_load_dwordx4 v[100:103], v[104:105], off offset:2048
	s_nop 0
	global_load_dwordx4 v[104:107], v[104:105], off offset:3072
	v_add_co_u32_e32 v54, vcc, s55, v64
	v_lshl_add_u64 v[58:59], s[94:95], 0, v[8:9]
	s_nop 0
	v_addc_co_u32_e32 v55, vcc, 0, v65, vcc
	v_add_co_u32_e32 v56, vcc, s53, v58
	s_add_i32 s0, s0, -1
	s_nop 0
	v_addc_co_u32_e32 v57, vcc, 0, v59, vcc
	v_add_co_u32_e32 v58, vcc, s54, v58
	v_lshl_add_u64 v[8:9], v[8:9], 0, s[38:39]
	s_nop 0
	v_addc_co_u32_e32 v59, vcc, 0, v59, vcc
	v_lshl_add_u64 v[10:11], v[10:11], 0, s[42:43]
	s_cmp_eq_u32 s0, 0
	s_waitcnt vmcnt(0)
	v_add_f32_e32 v41, v60, v61
	v_add_f32_e32 v49, v68, v69
	v_add_f32_e32 v41, v62, v41
	v_add_f32_e32 v51, v84, v85
	v_add_f32_e32 v49, v70, v49
	v_add_f32_e32 v41, v63, v41
	v_add_f32_e32 v53, v88, v89
	v_add_f32_e32 v51, v86, v51
	v_mov_b32_e32 v108, v92
	v_mov_b32_e32 v109, v96
	v_mov_b32_e32 v110, v93
	v_mov_b32_e32 v111, v97
	v_add_f32_e32 v49, v71, v49
	v_add_f32_e32 v41, 0, v41
	v_add_f32_e32 v53, v90, v53
	v_mov_b32_e32 v112, v94
	v_mov_b32_e32 v113, v98
	v_add_f32_e32 v51, v87, v51
	v_pk_add_f32 v[108:109], v[108:109], v[110:111]
	v_add_f32_e32 v41, v41, v49
	v_mov_b32_e32 v114, v95
	v_mov_b32_e32 v115, v99
	v_mov_b32_e32 v116, v100
	v_mov_b32_e32 v117, v104
	v_mov_b32_e32 v118, v101
	v_mov_b32_e32 v119, v105
	v_add_f32_e32 v53, v91, v53
	v_pk_add_f32 v[108:109], v[112:113], v[108:109]
	v_add_f32_e32 v41, v41, v51
	v_mov_b32_e32 v120, v102
	v_mov_b32_e32 v121, v106
	v_pk_add_f32 v[110:111], v[116:117], v[118:119]
	v_pk_add_f32 v[108:109], v[114:115], v[108:109]
	v_add_f32_e32 v41, v41, v53
	v_mov_b32_e32 v122, v103
	v_mov_b32_e32 v123, v107
	v_pk_add_f32 v[110:111], v[120:121], v[110:111]
	v_add_f32_e32 v41, v41, v108
	v_pk_add_f32 v[110:111], v[122:123], v[110:111]
	v_add_f32_e32 v41, v41, v109
	v_add_f32_e32 v41, v41, v110
	v_add_f32_e32 v41, v41, v111
	ds_bpermute_b32 v49, v72, v41
	s_waitcnt lgkmcnt(0)
	v_add_f32_e32 v41, v41, v49
	ds_bpermute_b32 v49, v73, v41
	s_waitcnt lgkmcnt(0)
	v_add_f32_e32 v41, v41, v49
	ds_bpermute_b32 v49, v74, v41
	s_waitcnt lgkmcnt(0)
	v_add_f32_e32 v41, v41, v49
	ds_bpermute_b32 v49, v75, v41
	s_waitcnt lgkmcnt(0)
	v_add_f32_e32 v41, v41, v49
	ds_bpermute_b32 v49, v76, v41
	s_waitcnt lgkmcnt(0)
	v_add_f32_e32 v41, v41, v49
	ds_bpermute_b32 v49, v77, v41
	s_waitcnt lgkmcnt(0)
	v_add_f32_e32 v41, v41, v49
	v_mul_f32_e32 v66, 0x3a000000, v41
	v_pk_add_f32 v[110:111], v[60:61], v[66:67] op_sel_hi:[1,0] neg_lo:[0,1] neg_hi:[0,1]
	v_pk_add_f32 v[108:109], v[62:63], v[66:67] op_sel_hi:[1,0] neg_lo:[0,1] neg_hi:[0,1]
	v_pk_add_f32 v[114:115], v[68:69], v[66:67] op_sel_hi:[1,0] neg_lo:[0,1] neg_hi:[0,1]
	v_pk_add_f32 v[68:69], v[102:103], v[66:67] op_sel_hi:[1,0] neg_lo:[0,1] neg_hi:[0,1]
	v_pk_mul_f32 v[102:103], v[110:111], v[110:111]
	v_pk_add_f32 v[112:113], v[70:71], v[66:67] op_sel_hi:[1,0] neg_lo:[0,1] neg_hi:[0,1]
	v_pk_add_f32 v[70:71], v[100:101], v[66:67] op_sel_hi:[1,0] neg_lo:[0,1] neg_hi:[0,1]
	v_pk_mul_f32 v[100:101], v[108:109], v[108:109]
	v_add_f32_e32 v41, v102, v103
	v_add_f32_e32 v41, v100, v41
	v_pk_add_f32 v[60:61], v[106:107], v[66:67] op_sel_hi:[1,0] neg_lo:[0,1] neg_hi:[0,1]
	v_pk_mul_f32 v[106:107], v[114:115], v[114:115]
	v_add_f32_e32 v41, v101, v41
	v_add_f32_e32 v41, v106, v41
	v_pk_add_f32 v[62:63], v[104:105], v[66:67] op_sel_hi:[1,0] neg_lo:[0,1] neg_hi:[0,1]
	v_pk_mul_f32 v[104:105], v[112:113], v[112:113]
	v_add_f32_e32 v41, v107, v41
	v_pk_add_f32 v[84:85], v[84:85], v[66:67] op_sel_hi:[1,0] neg_lo:[0,1] neg_hi:[0,1]
	v_add_f32_e32 v41, v104, v41
	v_pk_mul_f32 v[118:119], v[84:85], v[84:85]
	v_add_f32_e32 v41, v105, v41
	v_pk_add_f32 v[86:87], v[86:87], v[66:67] op_sel_hi:[1,0] neg_lo:[0,1] neg_hi:[0,1]
	v_add_f32_e32 v41, v118, v41
	v_pk_mul_f32 v[116:117], v[86:87], v[86:87]
	v_add_f32_e32 v41, v119, v41
	v_pk_add_f32 v[88:89], v[88:89], v[66:67] op_sel_hi:[1,0] neg_lo:[0,1] neg_hi:[0,1]
	v_add_f32_e32 v41, v116, v41
	v_pk_mul_f32 v[122:123], v[88:89], v[88:89]
	v_add_f32_e32 v41, v117, v41
	v_pk_add_f32 v[90:91], v[90:91], v[66:67] op_sel_hi:[1,0] neg_lo:[0,1] neg_hi:[0,1]
	v_add_f32_e32 v41, v122, v41
	v_pk_mul_f32 v[120:121], v[90:91], v[90:91]
	v_add_f32_e32 v41, v123, v41
	v_pk_add_f32 v[92:93], v[92:93], v[66:67] op_sel_hi:[1,0] neg_lo:[0,1] neg_hi:[0,1]
	v_add_f32_e32 v41, v120, v41
	v_pk_mul_f32 v[126:127], v[92:93], v[92:93]
	v_add_f32_e32 v41, v121, v41
	v_pk_add_f32 v[94:95], v[94:95], v[66:67] op_sel_hi:[1,0] neg_lo:[0,1] neg_hi:[0,1]
	v_add_f32_e32 v41, v126, v41
	v_pk_mul_f32 v[124:125], v[94:95], v[94:95]
	v_add_f32_e32 v41, v127, v41
	v_pk_add_f32 v[96:97], v[96:97], v[66:67] op_sel_hi:[1,0] neg_lo:[0,1] neg_hi:[0,1]
	v_add_f32_e32 v41, v124, v41
	v_pk_mul_f32 v[130:131], v[96:97], v[96:97]
	v_add_f32_e32 v41, v125, v41
	v_pk_add_f32 v[98:99], v[98:99], v[66:67] op_sel_hi:[1,0] neg_lo:[0,1] neg_hi:[0,1]
	v_add_f32_e32 v41, v130, v41
	v_pk_mul_f32 v[128:129], v[98:99], v[98:99]
	v_add_f32_e32 v41, v131, v41
	v_add_f32_e32 v41, v128, v41
	v_pk_mul_f32 v[134:135], v[70:71], v[70:71]
	v_add_f32_e32 v41, v129, v41
	v_add_f32_e32 v41, v134, v41
	v_pk_mul_f32 v[132:133], v[68:69], v[68:69]
	v_add_f32_e32 v41, v135, v41
	v_add_f32_e32 v41, v132, v41
	v_pk_mul_f32 v[138:139], v[62:63], v[62:63]
	v_add_f32_e32 v41, v133, v41
	v_add_f32_e32 v41, v138, v41
	v_pk_mul_f32 v[136:137], v[60:61], v[60:61]
	v_add_f32_e32 v41, v139, v41
	v_add_f32_e32 v41, v136, v41
	v_add_f32_e32 v41, v137, v41
	ds_bpermute_b32 v49, v72, v41
	s_waitcnt lgkmcnt(0)
	v_add_f32_e32 v41, v41, v49
	ds_bpermute_b32 v49, v73, v41
	s_waitcnt lgkmcnt(0)
	v_add_f32_e32 v41, v41, v49
	ds_bpermute_b32 v49, v74, v41
	s_waitcnt lgkmcnt(0)
	v_add_f32_e32 v41, v41, v49
	ds_bpermute_b32 v49, v75, v41
	s_waitcnt lgkmcnt(0)
	v_add_f32_e32 v41, v41, v49
	ds_bpermute_b32 v49, v76, v41
	s_waitcnt lgkmcnt(0)
	v_add_f32_e32 v41, v41, v49
	ds_bpermute_b32 v49, v77, v41
	s_waitcnt lgkmcnt(0)
	v_add_f32_e32 v41, v41, v49
	v_fmamk_f32 v41, v41, 0x3a000000, v45
	v_mul_f32_e32 v49, 0x4b800000, v41
	v_cmp_gt_f32_e32 vcc, s51, v41
	s_nop 1
	v_cndmask_b32_e32 v41, v41, v49, vcc
	v_rsq_f32_e32 v41, v41
	s_nop 0
	v_mul_f32_e32 v49, 0x45800000, v41
	v_cndmask_b32_e32 v66, v41, v49, vcc
	v_pk_mul_f32 v[100:101], v[110:111], v[66:67] op_sel_hi:[1,0]
	v_pk_mul_f32 v[102:103], v[108:109], v[66:67] op_sel_hi:[1,0]
	v_pk_fma_f32 v[0:1], v[0:1], v[100:101], v[4:5]
	v_pk_fma_f32 v[2:3], v[2:3], v[102:103], v[6:7]
	global_load_dwordx4 v[244:247], v[14:15], off offset:1024
	global_load_dwordx4 v[248:251], v[16:17], off offset:1024
	v_cvt_pk_bf16_f32 v4, v0, v1
	v_cvt_pk_bf16_f32 v5, v2, v3
	v_lshlrev_b32_e32 v6, 16, v4
	v_and_b32_e32 v7, 0xffff0000, v4
	v_lshlrev_b32_e32 v100, 16, v5
	v_and_b32_e32 v101, 0xffff0000, v5
	global_store_dwordx4 v[54:55], v[0:3], off offset:-4096
	global_store_dwordx2 v[56:57], v[4:5], off
	v_pk_mul_f32 v[102:103], v[112:113], v[66:67] op_sel_hi:[1,0]
	v_pk_add_f32 v[0:1], v[0:1], v[6:7] neg_lo:[0,1] neg_hi:[0,1]
	v_pk_add_f32 v[2:3], v[2:3], v[100:101] neg_lo:[0,1] neg_hi:[0,1]
	v_cvt_pk_bf16_f32 v0, v0, v1
	v_cvt_pk_bf16_f32 v1, v2, v3
	global_store_dwordx2 v[58:59], v[0:1], off
	s_nop 0
	v_pk_mul_f32 v[100:101], v[114:115], v[66:67] op_sel_hi:[1,0]
	v_add_co_u32_e32 v64, vcc, s52, v64
	v_pk_mul_f32 v[84:85], v[84:85], v[66:67] op_sel_hi:[1,0]
	s_nop 0
	v_addc_co_u32_e32 v65, vcc, 0, v65, vcc
	v_pk_mul_f32 v[86:87], v[86:87], v[66:67] op_sel_hi:[1,0]
	v_pk_mul_f32 v[68:69], v[68:69], v[66:67] op_sel_hi:[1,0]
	v_pk_mul_f32 v[62:63], v[62:63], v[66:67] op_sel_hi:[1,0]
	v_pk_mul_f32 v[60:61], v[60:61], v[66:67] op_sel_hi:[1,0]
	s_waitcnt vmcnt(3)
	v_pk_fma_f32 v[0:1], v[244:245], v[100:101], v[248:249]
	v_pk_fma_f32 v[2:3], v[246:247], v[102:103], v[250:251]
	global_load_dwordx4 v[244:247], v[14:15], off offset:2048
	global_load_dwordx4 v[248:251], v[16:17], off offset:2048
	v_cvt_pk_bf16_f32 v4, v0, v1
	v_cvt_pk_bf16_f32 v5, v2, v3
	v_lshlrev_b32_e32 v6, 16, v4
	v_and_b32_e32 v7, 0xffff0000, v4
	v_lshlrev_b32_e32 v100, 16, v5
	v_and_b32_e32 v101, 0xffff0000, v5
	global_store_dwordx4 v[64:65], v[0:3], off offset:1024
	global_store_dwordx2 v[56:57], v[4:5], off offset:512
	s_nop 0
	v_pk_add_f32 v[0:1], v[0:1], v[6:7] neg_lo:[0,1] neg_hi:[0,1]
	v_pk_add_f32 v[2:3], v[2:3], v[100:101] neg_lo:[0,1] neg_hi:[0,1]
	v_cvt_pk_bf16_f32 v0, v0, v1
	v_cvt_pk_bf16_f32 v1, v2, v3
	global_store_dwordx2 v[58:59], v[0:1], off offset:512
	s_nop 0
	s_waitcnt vmcnt(3)
	v_pk_fma_f32 v[0:1], v[244:245], v[84:85], v[248:249]
	v_pk_fma_f32 v[2:3], v[246:247], v[86:87], v[250:251]
	global_load_dwordx4 v[244:247], v[14:15], off offset:3072
	global_load_dwordx4 v[248:251], v[16:17], off offset:3072
	v_cvt_pk_bf16_f32 v4, v0, v1
	v_cvt_pk_bf16_f32 v5, v2, v3
	v_lshlrev_b32_e32 v6, 16, v4
	v_and_b32_e32 v7, 0xffff0000, v4
	v_lshlrev_b32_e32 v84, 16, v5
	v_and_b32_e32 v85, 0xffff0000, v5
	global_store_dwordx4 v[64:65], v[0:3], off offset:2048
	global_store_dwordx2 v[56:57], v[4:5], off offset:1024
	v_pk_mul_f32 v[86:87], v[90:91], v[66:67] op_sel_hi:[1,0]
	v_pk_add_f32 v[0:1], v[0:1], v[6:7] neg_lo:[0,1] neg_hi:[0,1]
	v_pk_add_f32 v[2:3], v[2:3], v[84:85] neg_lo:[0,1] neg_hi:[0,1]
	v_cvt_pk_bf16_f32 v0, v0, v1
	v_cvt_pk_bf16_f32 v1, v2, v3
	global_store_dwordx2 v[58:59], v[0:1], off offset:1024
	s_nop 0
	v_pk_mul_f32 v[84:85], v[88:89], v[66:67] op_sel_hi:[1,0]
	s_waitcnt vmcnt(3)
	v_pk_fma_f32 v[2:3], v[246:247], v[86:87], v[250:251]
	v_pk_fma_f32 v[0:1], v[244:245], v[84:85], v[248:249]
	global_load_dwordx4 v[244:247], v[18:19], off
	global_load_dwordx4 v[248:251], v[20:21], off
	v_cvt_pk_bf16_f32 v5, v2, v3
	v_cvt_pk_bf16_f32 v4, v0, v1
	global_store_dwordx4 v[64:65], v[0:3], off offset:3072
	v_lshlrev_b32_e32 v6, 16, v4
	v_and_b32_e32 v7, 0xffff0000, v4
	v_lshlrev_b32_e32 v64, 16, v5
	v_and_b32_e32 v65, 0xffff0000, v5
	v_pk_add_f32 v[0:1], v[0:1], v[6:7] neg_lo:[0,1] neg_hi:[0,1]
	v_pk_add_f32 v[2:3], v[2:3], v[64:65] neg_lo:[0,1] neg_hi:[0,1]
	v_cvt_pk_bf16_f32 v0, v0, v1
	v_cvt_pk_bf16_f32 v1, v2, v3
	global_store_dwordx2 v[56:57], v[4:5], off offset:1536
	global_store_dwordx2 v[58:59], v[0:1], off offset:1536
	s_nop 0
	v_pk_mul_f32 v[64:65], v[92:93], v[66:67] op_sel_hi:[1,0]
	v_pk_mul_f32 v[84:85], v[94:95], v[66:67] op_sel_hi:[1,0]
	s_waitcnt vmcnt(3)
	v_pk_fma_f32 v[0:1], v[244:245], v[64:65], v[248:249]
	v_pk_fma_f32 v[2:3], v[246:247], v[84:85], v[250:251]
	global_load_dwordx4 v[244:247], v[22:23], off
	global_load_dwordx4 v[248:251], v[24:25], off
	v_cvt_pk_bf16_f32 v4, v0, v1
	v_cvt_pk_bf16_f32 v5, v2, v3
	v_lshlrev_b32_e32 v6, 16, v4
	v_and_b32_e32 v7, 0xffff0000, v4
	v_lshlrev_b32_e32 v64, 16, v5
	v_and_b32_e32 v65, 0xffff0000, v5
	global_store_dwordx4 v[54:55], v[0:3], off
	global_store_dwordx2 v[56:57], v[4:5], off offset:2048
	v_pk_mul_f32 v[84:85], v[98:99], v[66:67] op_sel_hi:[1,0]
	v_pk_add_f32 v[0:1], v[0:1], v[6:7] neg_lo:[0,1] neg_hi:[0,1]
	v_pk_add_f32 v[2:3], v[2:3], v[64:65] neg_lo:[0,1] neg_hi:[0,1]
	v_cvt_pk_bf16_f32 v0, v0, v1
	v_cvt_pk_bf16_f32 v1, v2, v3
	global_store_dwordx2 v[58:59], v[0:1], off offset:2048
	s_nop 0
	v_pk_mul_f32 v[64:65], v[96:97], v[66:67] op_sel_hi:[1,0]
	s_waitcnt vmcnt(3)
	v_pk_fma_f32 v[2:3], v[246:247], v[84:85], v[250:251]
	v_pk_fma_f32 v[0:1], v[244:245], v[64:65], v[248:249]
	global_load_dwordx4 v[244:247], v[26:27], off
	global_load_dwordx4 v[248:251], v[28:29], off
	v_cvt_pk_bf16_f32 v5, v2, v3
	v_cvt_pk_bf16_f32 v4, v0, v1
	v_lshlrev_b32_e32 v6, 16, v4
	v_and_b32_e32 v7, 0xffff0000, v4
	v_lshlrev_b32_e32 v64, 16, v5
	v_and_b32_e32 v65, 0xffff0000, v5
	global_store_dwordx4 v[54:55], v[0:3], off offset:1024
	global_store_dwordx2 v[56:57], v[4:5], off offset:2560
	s_nop 0
	v_pk_add_f32 v[0:1], v[0:1], v[6:7] neg_lo:[0,1] neg_hi:[0,1]
	v_pk_add_f32 v[2:3], v[2:3], v[64:65] neg_lo:[0,1] neg_hi:[0,1]
	v_cvt_pk_bf16_f32 v0, v0, v1
	v_cvt_pk_bf16_f32 v1, v2, v3
	global_store_dwordx2 v[58:59], v[0:1], off offset:2560
	s_nop 0
	v_pk_mul_f32 v[64:65], v[70:71], v[66:67] op_sel_hi:[1,0]
	s_waitcnt vmcnt(3)
	v_pk_fma_f32 v[2:3], v[246:247], v[68:69], v[250:251]
	v_pk_fma_f32 v[0:1], v[244:245], v[64:65], v[248:249]
	global_load_dwordx4 v[244:247], v[30:31], off
	global_load_dwordx4 v[248:251], v[32:33], off
	v_cvt_pk_bf16_f32 v5, v2, v3
	v_cvt_pk_bf16_f32 v4, v0, v1
	v_lshlrev_b32_e32 v6, 16, v4
	v_and_b32_e32 v7, 0xffff0000, v4
	v_lshlrev_b32_e32 v64, 16, v5
	v_and_b32_e32 v65, 0xffff0000, v5
	global_store_dwordx4 v[54:55], v[0:3], off offset:2048
	global_store_dwordx2 v[56:57], v[4:5], off offset:3072
	s_nop 0
	v_pk_add_f32 v[0:1], v[0:1], v[6:7] neg_lo:[0,1] neg_hi:[0,1]
	v_pk_add_f32 v[2:3], v[2:3], v[64:65] neg_lo:[0,1] neg_hi:[0,1]
	v_cvt_pk_bf16_f32 v0, v0, v1
	v_cvt_pk_bf16_f32 v1, v2, v3
	global_store_dwordx2 v[58:59], v[0:1], off offset:3072
	s_nop 0
	s_waitcnt vmcnt(3)
	v_pk_fma_f32 v[0:1], v[62:63], v[244:245], v[248:249]
	v_pk_fma_f32 v[2:3], v[60:61], v[246:247], v[250:251]
	v_cvt_pk_bf16_f32 v4, v0, v1
	v_cvt_pk_bf16_f32 v5, v2, v3
	global_store_dwordx4 v[54:55], v[0:3], off offset:3072
	v_lshlrev_b32_e32 v6, 16, v4
	v_and_b32_e32 v7, 0xffff0000, v4
	v_lshlrev_b32_e32 v54, 16, v5
	v_and_b32_e32 v55, 0xffff0000, v5
	v_pk_add_f32 v[0:1], v[0:1], v[6:7] neg_lo:[0,1] neg_hi:[0,1]
	v_pk_add_f32 v[2:3], v[2:3], v[54:55] neg_lo:[0,1] neg_hi:[0,1]
	v_cvt_pk_bf16_f32 v0, v0, v1
	v_cvt_pk_bf16_f32 v1, v2, v3
	global_store_dwordx2 v[56:57], v[4:5], off offset:3584
	global_store_dwordx2 v[58:59], v[0:1], off offset:3584
	s_cbranch_scc0 .LBB0_849
	v_ashrrev_i32_e32 v49, 31, v48
	v_lshlrev_b64 v[0:1], 12, v[48:49]
	s_lshl_b32 s60, s59, 4
	v_lshl_add_u64 v[54:55], v[46:47], 0, v[0:1]
	v_or_b32_e32 v0, s60, v43
	v_ashrrev_i32_e32 v1, 31, v0
	v_readlane_b32 s0, v242, 50
	v_lshlrev_b64 v[0:1], 12, v[0:1]
	v_readlane_b32 s1, v242, 51
	v_lshl_add_u64 v[58:59], s[30:31], 0, v[0:1]
	s_nop 0
	v_lshl_add_u64 v[56:57], s[0:1], 0, v[0:1]
	v_mov_b32_e32 v0, 0
	s_mov_b32 s0, 0
	v_mov_b32_e32 v1, v0
	v_mov_b32_e32 v2, v0
	v_mov_b32_e32 v3, v0
	v_mov_b32_e32 v4, v0
	v_mov_b32_e32 v5, v0
	v_mov_b32_e32 v6, v0
	v_mov_b32_e32 v7, v0
	v_mov_b32_e32 v8, v0
	v_mov_b32_e32 v9, v0
	v_mov_b32_e32 v10, v0
	v_mov_b32_e32 v11, v0
	s_barrier
